# attA unit epilogue: the 16 output-gain vector loads keep their order but the first 4 are issued before the first epilogue barrier into registers free after the tile loop, the next 6 right after the di
# baseline (speedup 1.0000x reference)
; #define LAS __attribute__((address_space(3)))
; __device__ __forceinline__ void unit(LAS unsigned char* lds, bf16_t* P1, const bf16_t* vaT, int b, int h, int qblk, float lam, const float* subln_w, const float* khalf) {
;     ...
;     asm volatile("s_waitcnt vmcnt(0) lgkmcnt(0)\n\ts_barrier" ::: "memory");
;     const float lt = l + __shfl_xor(l, 32); const float inv = 1.f / lt;
;     LAS float* X = (LAS float*)(lds + XOFF);
;     const int ql = qs * 32 + r32;
;     if (mi == 1) { const float sc = inv * lam;
; #pragma unroll
;         for (int d = 0; d < 4; ++d)
; #pragma unroll
;             for (int g4 = 0; g4 < 4; ++g4) { const f32x4 v = (f32x4){O[d][4 * g4], O[d][4 * g4 + 1], O[d][4 * g4 + 2], O[d][4 * g4 + 3]} * sc;
;                 *(LAS f32x4*)(X + ql * XP + d * 32 + g4 * 8 + hi * 4) = v; } }
;     __syncthreads();
;     if (mi == 0) { float ss = 0.f;
; #pragma unroll
;         for (int d = 0; d < 4; ++d)
; #pragma unroll
;             for (int g4 = 0; g4 < 4; ++g4) { const f32x4 xv = *(const LAS f32x4*)(X + ql * XP + d * 32 + g4 * 8 + hi * 4);
; #pragma unroll
;                 for (int e = 0; e < 4; ++e) { const float dv = O[d][4 * g4 + e] * inv - xv[e]; O[d][4 * g4 + e] = dv; ss += dv * dv; } }
.LBB0_420:
	ds_bpermute_b32 v0, v115, v191
	s_waitcnt vmcnt(0) lgkmcnt(0)
	s_cmpk_gt_u32 s61, 0xff
	s_cbranch_scc1 .La_epi_noload
	global_load_dwordx4 v[236:239], v[118:119], off
	global_load_dwordx4 v[244:247], v[118:119], off offset:32
	global_load_dwordx4 v[248:251], v[118:119], off offset:64
	global_load_dwordx4 v[252:255], v[118:119], off offset:96
.La_epi_noload:
	s_barrier
	s_cmp_lg_u32 s70, 1
	s_waitcnt lgkmcnt(0)
	v_add_f32_e32 v0, v191, v0
	v_div_scale_f32 v66, s[2:3], v0, v0, 1.0
	v_rcp_f32_e32 v67, v66
	v_div_scale_f32 v68, vcc, 1.0, v0, 1.0
	s_movk_i32 s2, 0x210
	v_fma_f32 v69, -v66, v67, 1.0
	v_fmac_f32_e32 v67, v69, v67
	v_mul_f32_e32 v69, v68, v67
	v_fma_f32 v70, -v66, v69, v68
	v_fmac_f32_e32 v69, v70, v67
	v_fma_f32 v66, -v66, v69, v68
	v_div_fmas_f32 v66, v66, v67, v69
	v_div_fixup_f32 v0, v66, v0, 1.0
	v_mad_u32_u24 v66, v123, s2, v152
	s_cbranch_scc1 .LBB0_422
	v_mul_f32_e32 v72, v117, v0
	v_pk_mul_f32 v[70:71], v[52:53], v[72:73] op_sel_hi:[1,0]
	v_pk_mul_f32 v[68:69], v[50:51], v[72:73] op_sel_hi:[1,0]
	ds_write_b128 v66, v[68:71]
	v_pk_mul_f32 v[70:71], v[56:57], v[72:73] op_sel_hi:[1,0]
	v_pk_mul_f32 v[68:69], v[54:55], v[72:73] op_sel_hi:[1,0]
	ds_write_b128 v66, v[68:71] offset:32
	v_pk_mul_f32 v[70:71], v[60:61], v[72:73] op_sel_hi:[1,0]
	v_pk_mul_f32 v[68:69], v[58:59], v[72:73] op_sel_hi:[1,0]
	ds_write_b128 v66, v[68:71] offset:64
	v_pk_mul_f32 v[70:71], v[64:65], v[72:73] op_sel_hi:[1,0]
	v_pk_mul_f32 v[68:69], v[62:63], v[72:73] op_sel_hi:[1,0]
	ds_write_b128 v66, v[68:71] offset:96
	v_pk_mul_f32 v[70:71], v[36:37], v[72:73] op_sel_hi:[1,0]
	v_pk_mul_f32 v[68:69], v[34:35], v[72:73] op_sel_hi:[1,0]
	ds_write_b128 v66, v[68:71] offset:128
	v_pk_mul_f32 v[70:71], v[40:41], v[72:73] op_sel_hi:[1,0]
	v_pk_mul_f32 v[68:69], v[38:39], v[72:73] op_sel_hi:[1,0]
	ds_write_b128 v66, v[68:71] offset:160
	v_pk_mul_f32 v[70:71], v[44:45], v[72:73] op_sel_hi:[1,0]
	v_pk_mul_f32 v[68:69], v[42:43], v[72:73] op_sel_hi:[1,0]
	ds_write_b128 v66, v[68:71] offset:192
	v_pk_mul_f32 v[70:71], v[48:49], v[72:73] op_sel_hi:[1,0]
	v_pk_mul_f32 v[68:69], v[46:47], v[72:73] op_sel_hi:[1,0]
	ds_write_b128 v66, v[68:71] offset:224
	v_pk_mul_f32 v[70:71], v[20:21], v[72:73] op_sel_hi:[1,0]
	v_pk_mul_f32 v[68:69], v[18:19], v[72:73] op_sel_hi:[1,0]
	ds_write_b128 v66, v[68:71] offset:256
	v_pk_mul_f32 v[70:71], v[24:25], v[72:73] op_sel_hi:[1,0]
	v_pk_mul_f32 v[68:69], v[22:23], v[72:73] op_sel_hi:[1,0]
	ds_write_b128 v66, v[68:71] offset:288
	v_pk_mul_f32 v[70:71], v[28:29], v[72:73] op_sel_hi:[1,0]
	v_pk_mul_f32 v[68:69], v[26:27], v[72:73] op_sel_hi:[1,0]
	ds_write_b128 v66, v[68:71] offset:320
	v_pk_mul_f32 v[70:71], v[32:33], v[72:73] op_sel_hi:[1,0]
	v_pk_mul_f32 v[68:69], v[30:31], v[72:73] op_sel_hi:[1,0]
	ds_write_b128 v66, v[68:71] offset:352
	v_pk_mul_f32 v[70:71], v[4:5], v[72:73] op_sel_hi:[1,0]
	v_pk_mul_f32 v[68:69], v[2:3], v[72:73] op_sel_hi:[1,0]
	ds_write_b128 v66, v[68:71] offset:384
	v_pk_mul_f32 v[70:71], v[8:9], v[72:73] op_sel_hi:[1,0]
	v_pk_mul_f32 v[68:69], v[6:7], v[72:73] op_sel_hi:[1,0]
	ds_write_b128 v66, v[68:71] offset:416
	v_pk_mul_f32 v[70:71], v[12:13], v[72:73] op_sel_hi:[1,0]
	v_pk_mul_f32 v[68:69], v[10:11], v[72:73] op_sel_hi:[1,0]
	ds_write_b128 v66, v[68:71] offset:448
	v_pk_mul_f32 v[70:71], v[16:17], v[72:73] op_sel_hi:[1,0]
	v_pk_mul_f32 v[68:69], v[14:15], v[72:73] op_sel_hi:[1,0]
	ds_write_b128 v66, v[68:71] offset:480
.LBB0_422:
	s_cmpk_gt_u32 s61, 0xff
	s_waitcnt lgkmcnt(0)
	s_barrier
	s_cbranch_scc1 .LBB0_383
	ds_read_b128 v[74:77], v66
	ds_read_b128 v[78:81], v66 offset:32
	ds_read_b128 v[82:85], v66 offset:64
	ds_read_b128 v[86:89], v66 offset:96
	ds_read_b128 v[130:133], v66 offset:128
	ds_read_b128 v[134:137], v66 offset:160
	ds_read_b128 v[138:141], v66 offset:192
	ds_read_b128 v[186:189], v66 offset:224
	ds_read_b128 v[190:193], v66 offset:256
	ds_read_b128 v[194:197], v66 offset:288
	ds_read_b128 v[202:205], v66 offset:448
	ds_read_b128 v[70:73], v66 offset:480
	ds_read_b128 v[206:209], v66 offset:320
	ds_read_b128 v[210:213], v66 offset:352
	ds_read_b128 v[214:217], v66 offset:384
	ds_read_b128 v[218:221], v66 offset:416
	s_waitcnt lgkmcnt(14)
	v_pk_fma_f32 v[94:95], v[50:51], v[0:1], v[74:75] op_sel_hi:[1,0,1] neg_lo:[0,0,1] neg_hi:[0,0,1]
	v_pk_fma_f32 v[90:91], v[52:53], v[0:1], v[76:77] op_sel_hi:[1,0,1] neg_lo:[0,0,1] neg_hi:[0,0,1]
	v_pk_mul_f32 v[142:143], v[94:95], v[94:95]
	s_waitcnt lgkmcnt(4)
	v_pk_fma_f32 v[70:71], v[14:15], v[0:1], v[70:71] op_sel_hi:[1,0,1] neg_lo:[0,0,1] neg_hi:[0,0,1]
	v_pk_fma_f32 v[72:73], v[16:17], v[0:1], v[72:73] op_sel_hi:[1,0,1] neg_lo:[0,0,1] neg_hi:[0,0,1]
	v_pk_mul_f32 v[112:113], v[90:91], v[90:91]
	v_pk_fma_f32 v[92:93], v[56:57], v[0:1], v[80:81] op_sel_hi:[1,0,1] neg_lo:[0,0,1] neg_hi:[0,0,1]
	v_pk_fma_f32 v[98:99], v[54:55], v[0:1], v[78:79] op_sel_hi:[1,0,1] neg_lo:[0,0,1] neg_hi:[0,0,1]
	v_pk_fma_f32 v[96:97], v[60:61], v[0:1], v[84:85] op_sel_hi:[1,0,1] neg_lo:[0,0,1] neg_hi:[0,0,1]
	v_pk_fma_f32 v[106:107], v[58:59], v[0:1], v[82:83] op_sel_hi:[1,0,1] neg_lo:[0,0,1] neg_hi:[0,0,1]
	v_pk_fma_f32 v[102:103], v[64:65], v[0:1], v[88:89] op_sel_hi:[1,0,1] neg_lo:[0,0,1] neg_hi:[0,0,1]
	v_pk_fma_f32 v[108:109], v[62:63], v[0:1], v[86:87] op_sel_hi:[1,0,1] neg_lo:[0,0,1] neg_hi:[0,0,1]
	v_pk_fma_f32 v[62:63], v[36:37], v[0:1], v[132:133] op_sel_hi:[1,0,1] neg_lo:[0,0,1] neg_hi:[0,0,1]
	v_pk_fma_f32 v[64:65], v[34:35], v[0:1], v[130:131] op_sel_hi:[1,0,1] neg_lo:[0,0,1] neg_hi:[0,0,1]
	v_pk_fma_f32 v[74:75], v[40:41], v[0:1], v[136:137] op_sel_hi:[1,0,1] neg_lo:[0,0,1] neg_hi:[0,0,1]
	v_pk_fma_f32 v[76:77], v[38:39], v[0:1], v[134:135] op_sel_hi:[1,0,1] neg_lo:[0,0,1] neg_hi:[0,0,1]
	v_pk_fma_f32 v[78:79], v[44:45], v[0:1], v[140:141] op_sel_hi:[1,0,1] neg_lo:[0,0,1] neg_hi:[0,0,1]
	v_pk_fma_f32 v[80:81], v[42:43], v[0:1], v[138:139] op_sel_hi:[1,0,1] neg_lo:[0,0,1] neg_hi:[0,0,1]
	v_pk_fma_f32 v[82:83], v[48:49], v[0:1], v[188:189] op_sel_hi:[1,0,1] neg_lo:[0,0,1] neg_hi:[0,0,1]
	v_pk_fma_f32 v[84:85], v[46:47], v[0:1], v[186:187] op_sel_hi:[1,0,1] neg_lo:[0,0,1] neg_hi:[0,0,1]
	v_pk_fma_f32 v[86:87], v[20:21], v[0:1], v[192:193] op_sel_hi:[1,0,1] neg_lo:[0,0,1] neg_hi:[0,0,1]
	v_pk_fma_f32 v[88:89], v[18:19], v[0:1], v[190:191] op_sel_hi:[1,0,1] neg_lo:[0,0,1] neg_hi:[0,0,1]
	v_pk_fma_f32 v[24:25], v[24:25], v[0:1], v[196:197] op_sel_hi:[1,0,1] neg_lo:[0,0,1] neg_hi:[0,0,1]
	v_pk_fma_f32 v[22:23], v[22:23], v[0:1], v[194:195] op_sel_hi:[1,0,1] neg_lo:[0,0,1] neg_hi:[0,0,1]
	s_waitcnt lgkmcnt(3)
; __device__ __forceinline__ unsigned cvtpk(float lo, float hi) { return pg8::cvt_pk_bf16(lo, hi); }
; __device__ __forceinline__ void unit(LAS unsigned char* lds, bf16_t* P1, const bf16_t* vaT, int b, int h, int qblk, float lam, const float* subln_w, const float* khalf) {
;     ...
;                 for (int e = 0; e < 4; ++e) { const float dv = O[d][4 * g4 + e] * inv - xv[e]; O[d][4 * g4 + e] = dv; ss += dv * dv; } }
;         ss += __shfl_xor(ss, 32);
;         const float rinv = rsqrtf(ss * (1.f / 128.f) + LN_EPS) * 0.8f;
; #pragma unroll
;         for (int d = 0; d < 4; ++d)
; #pragma unroll
;             for (int g4 = 0; g4 < 4; ++g4) { const int d0 = d * 32 + g4 * 8 + hi * 4; const f32x4 w = *(const f32x4*)(subln_w + d0);
;                 u32x2 o; o.x = cvtpk(O[d][4 * g4] * rinv * w[0], O[d][4 * g4 + 1] * rinv * w[1]); o.y = cvtpk(O[d][4 * g4 + 2] * rinv * w[2], O[d][4 * g4 + 3] * rinv * w[3]);
	v_pk_fma_f32 v[28:29], v[28:29], v[0:1], v[208:209] op_sel_hi:[1,0,1] neg_lo:[0,0,1] neg_hi:[0,0,1]
	v_pk_fma_f32 v[26:27], v[26:27], v[0:1], v[206:207] op_sel_hi:[1,0,1] neg_lo:[0,0,1] neg_hi:[0,0,1]
	s_waitcnt lgkmcnt(2)
	v_pk_fma_f32 v[32:33], v[32:33], v[0:1], v[212:213] op_sel_hi:[1,0,1] neg_lo:[0,0,1] neg_hi:[0,0,1]
	v_pk_fma_f32 v[30:31], v[30:31], v[0:1], v[210:211] op_sel_hi:[1,0,1] neg_lo:[0,0,1] neg_hi:[0,0,1]
	s_waitcnt lgkmcnt(1)
	v_pk_fma_f32 v[4:5], v[4:5], v[0:1], v[216:217] op_sel_hi:[1,0,1] neg_lo:[0,0,1] neg_hi:[0,0,1]
	v_pk_fma_f32 v[2:3], v[2:3], v[0:1], v[214:215] op_sel_hi:[1,0,1] neg_lo:[0,0,1] neg_hi:[0,0,1]
	s_waitcnt lgkmcnt(0)
	v_pk_fma_f32 v[8:9], v[8:9], v[0:1], v[220:221] op_sel_hi:[1,0,1] neg_lo:[0,0,1] neg_hi:[0,0,1]
	v_pk_fma_f32 v[6:7], v[6:7], v[0:1], v[218:219] op_sel_hi:[1,0,1] neg_lo:[0,0,1] neg_hi:[0,0,1]
	v_pk_fma_f32 v[12:13], v[12:13], v[0:1], v[204:205] op_sel_hi:[1,0,1] neg_lo:[0,0,1] neg_hi:[0,0,1]
	v_pk_fma_f32 v[10:11], v[10:11], v[0:1], v[202:203] op_sel_hi:[1,0,1] neg_lo:[0,0,1] neg_hi:[0,0,1]
	global_load_dwordx4 v[34:37], v[118:119], off offset:128
	global_load_dwordx4 v[14:17], v[118:119], off offset:160
	global_load_dwordx4 v[42:45], v[118:119], off offset:192
	global_load_dwordx4 v[38:41], v[118:119], off offset:224
	global_load_dwordx4 v[46:49], v[118:119], off offset:256
	global_load_dwordx4 v[18:21], v[118:119], off offset:288
	v_add_f32_e32 v0, v142, v143
	v_add_f32_e32 v0, v112, v0
	v_pk_mul_f32 v[222:223], v[98:99], v[98:99]
	v_add_f32_e32 v0, v113, v0
	v_add_f32_e32 v0, v222, v0
	v_pk_mul_f32 v[198:199], v[92:93], v[92:93]
	v_add_f32_e32 v0, v223, v0
	v_add_f32_e32 v0, v198, v0
	v_pk_mul_f32 v[226:227], v[106:107], v[106:107]
	v_add_f32_e32 v0, v199, v0
	v_add_f32_e32 v0, v226, v0
	v_pk_mul_f32 v[224:225], v[96:97], v[96:97]
	v_add_f32_e32 v0, v227, v0
	v_add_f32_e32 v0, v224, v0
	v_pk_mul_f32 v[230:231], v[108:109], v[108:109]
	v_add_f32_e32 v0, v225, v0
	v_add_f32_e32 v0, v230, v0
	v_pk_mul_f32 v[228:229], v[102:103], v[102:103]
	v_add_f32_e32 v0, v231, v0
	v_add_f32_e32 v0, v228, v0
	v_pk_mul_f32 v[130:131], v[64:65], v[64:65]
	v_add_f32_e32 v0, v229, v0
	v_add_f32_e32 v0, v130, v0
	v_pk_mul_f32 v[132:133], v[62:63], v[62:63]
	v_add_f32_e32 v0, v131, v0
	v_add_f32_e32 v0, v132, v0
	v_pk_mul_f32 v[134:135], v[76:77], v[76:77]
	v_add_f32_e32 v0, v133, v0
	v_add_f32_e32 v0, v134, v0
	v_pk_mul_f32 v[136:137], v[74:75], v[74:75]
	v_add_f32_e32 v0, v135, v0
	v_add_f32_e32 v0, v136, v0
	v_pk_mul_f32 v[138:139], v[80:81], v[80:81]
	v_add_f32_e32 v0, v137, v0
	v_add_f32_e32 v0, v138, v0
	v_pk_mul_f32 v[140:141], v[78:79], v[78:79]
	v_add_f32_e32 v0, v139, v0
	v_add_f32_e32 v0, v140, v0
	v_pk_mul_f32 v[186:187], v[84:85], v[84:85]
	v_add_f32_e32 v0, v141, v0
	v_add_f32_e32 v0, v186, v0
	v_pk_mul_f32 v[188:189], v[82:83], v[82:83]
	v_add_f32_e32 v0, v187, v0
	v_add_f32_e32 v0, v188, v0
	v_pk_mul_f32 v[190:191], v[88:89], v[88:89]
	v_add_f32_e32 v0, v189, v0
	v_add_f32_e32 v0, v190, v0
	v_pk_mul_f32 v[192:193], v[86:87], v[86:87]
	v_add_f32_e32 v0, v191, v0
	v_add_f32_e32 v0, v192, v0
	v_pk_mul_f32 v[194:195], v[22:23], v[22:23]
	v_add_f32_e32 v0, v193, v0
	v_add_f32_e32 v0, v194, v0
	v_pk_mul_f32 v[196:197], v[24:25], v[24:25]
	v_add_f32_e32 v0, v195, v0
	v_add_f32_e32 v0, v196, v0
	v_pk_mul_f32 v[206:207], v[26:27], v[26:27]
	v_add_f32_e32 v0, v197, v0
	v_add_f32_e32 v0, v206, v0
	v_pk_mul_f32 v[208:209], v[28:29], v[28:29]
	v_add_f32_e32 v0, v207, v0
	v_add_f32_e32 v0, v208, v0
	v_pk_mul_f32 v[210:211], v[30:31], v[30:31]
	v_add_f32_e32 v0, v209, v0
	v_add_f32_e32 v0, v210, v0
	v_pk_mul_f32 v[212:213], v[32:33], v[32:33]
	v_add_f32_e32 v0, v211, v0
	v_add_f32_e32 v0, v212, v0
	v_pk_mul_f32 v[214:215], v[2:3], v[2:3]
	v_add_f32_e32 v0, v213, v0
	v_add_f32_e32 v0, v214, v0
	v_pk_mul_f32 v[216:217], v[4:5], v[4:5]
	v_add_f32_e32 v0, v215, v0
	v_add_f32_e32 v0, v216, v0
	v_pk_mul_f32 v[218:219], v[6:7], v[6:7]
	v_add_f32_e32 v0, v217, v0
	v_add_f32_e32 v0, v218, v0
	v_pk_mul_f32 v[220:221], v[8:9], v[8:9]
	v_add_f32_e32 v0, v219, v0
	v_add_f32_e32 v0, v220, v0
	v_pk_mul_f32 v[202:203], v[10:11], v[10:11]
	v_add_f32_e32 v0, v221, v0
	v_add_f32_e32 v0, v202, v0
	v_pk_mul_f32 v[204:205], v[12:13], v[12:13]
	v_add_f32_e32 v0, v203, v0
	v_add_f32_e32 v0, v204, v0
	v_pk_mul_f32 v[100:101], v[70:71], v[70:71]
	v_add_f32_e32 v0, v205, v0
	v_add_f32_e32 v0, v100, v0
	v_pk_mul_f32 v[104:105], v[72:73], v[72:73]
	v_add_f32_e32 v0, v101, v0
	v_add_f32_e32 v0, v104, v0
	v_add_f32_e32 v0, v105, v0
	ds_bpermute_b32 v100, v115, v0
	v_mov_b32_e32 v240, s46
	s_movk_i32 s2, 0x110
	v_mad_u32_u24 v110, v123, s2, v240
	s_mov_b32 s2, 0x800000
	s_waitcnt lgkmcnt(0)
	v_add_f32_e32 v0, v0, v100
	v_fmamk_f32 v0, v0, 0x3c000000, v180
	v_mul_f32_e32 v100, 0x4b800000, v0
	v_cmp_gt_f32_e32 vcc, s2, v0
	v_cndmask_b32_e32 v0, v0, v100, vcc
	v_rsq_f32_e32 v0, v0
	v_add_u32_e32 v111, v110, v116
	global_load_dwordx4 v[130:133], v[118:119], off offset:320
	global_load_dwordx4 v[134:137], v[118:119], off offset:352
	v_mul_f32_e32 v105, 0x45800000, v0
	v_cndmask_b32_e32 v0, v0, v105, vcc
	v_mul_f32_e32 v0, 0x3f4ccccd, v0
	v_pk_mul_f32 v[94:95], v[94:95], v[0:1] op_sel_hi:[1,0]
	v_pk_mul_f32 v[90:91], v[90:91], v[0:1] op_sel_hi:[1,0]
	s_waitcnt vmcnt(11)
; #define LAS __attribute__((address_space(3)))
; __device__ __forceinline__ unsigned cvtpk(float lo, float hi) { return pg8::cvt_pk_bf16(lo, hi); }
; __device__ __forceinline__ void unit(LAS unsigned char* lds, bf16_t* P1, const bf16_t* vaT, int b, int h, int qblk, float lam, const float* subln_w, const float* khalf) {
;     ...
; #pragma unroll
;         for (int d = 0; d < 4; ++d)
; #pragma unroll
;             for (int g4 = 0; g4 < 4; ++g4) { const int d0 = d * 32 + g4 * 8 + hi * 4; const f32x4 w = *(const f32x4*)(subln_w + d0);
;                 u32x2 o; o.x = cvtpk(O[d][4 * g4] * rinv * w[0], O[d][4 * g4 + 1] * rinv * w[1]); o.y = cvtpk(O[d][4 * g4 + 2] * rinv * w[2], O[d][4 * g4 + 3] * rinv * w[3]);
;                 *(LAS u32x2*)(lds + 69632 + ql * 272 + d0 * 2) = o; } }
	v_pk_mul_f32 v[66:67], v[236:237], v[94:95]
	v_pk_mul_f32 v[68:69], v[238:239], v[90:91]
	v_cvt_pk_bf16_f32 v66, v66, v67
	v_cvt_pk_bf16_f32 v67, v68, v69
	global_load_dwordx4 v[138:141], v[118:119], off offset:384
	global_load_dwordx4 v[186:189], v[118:119], off offset:416
	ds_write_b64 v111, v[66:67]
	v_pk_mul_f32 v[66:67], v[98:99], v[0:1] op_sel_hi:[1,0]
	v_add_u32_e32 v120, v110, v153
	s_waitcnt vmcnt(12)
	v_pk_mul_f32 v[50:51], v[244:245], v[66:67]
	v_pk_mul_f32 v[66:67], v[92:93], v[0:1] op_sel_hi:[1,0]
	v_cvt_pk_bf16_f32 v50, v50, v51
	v_pk_mul_f32 v[52:53], v[246:247], v[66:67]
	v_add_u32_e32 v123, v110, v154
	v_cvt_pk_bf16_f32 v51, v52, v53
	ds_write_b64 v120, v[50:51]
	v_pk_mul_f32 v[50:51], v[106:107], v[0:1] op_sel_hi:[1,0]
	v_pk_mul_f32 v[52:53], v[96:97], v[0:1] op_sel_hi:[1,0]
	s_waitcnt vmcnt(11)
	v_pk_mul_f32 v[50:51], v[248:249], v[50:51]
	v_pk_mul_f32 v[52:53], v[250:251], v[52:53]
	v_cvt_pk_bf16_f32 v50, v50, v51
	v_cvt_pk_bf16_f32 v51, v52, v53
	global_load_dwordx4 v[190:193], v[118:119], off offset:448
	ds_write_b64 v123, v[50:51]
	v_pk_mul_f32 v[50:51], v[108:109], v[0:1] op_sel_hi:[1,0]
	v_pk_mul_f32 v[52:53], v[102:103], v[0:1] op_sel_hi:[1,0]
	s_waitcnt vmcnt(11)
	v_pk_mul_f32 v[50:51], v[252:253], v[50:51]
	v_pk_mul_f32 v[52:53], v[254:255], v[52:53]
	v_add_u32_e32 v125, v110, v155
	v_cvt_pk_bf16_f32 v50, v50, v51
	v_cvt_pk_bf16_f32 v51, v52, v53
	ds_write_b64 v125, v[50:51]
	global_load_dwordx4 v[50:53], v[118:119], off offset:480
	v_pk_mul_f32 v[54:55], v[64:65], v[0:1] op_sel_hi:[1,0]
	v_add_u32_e32 v127, v110, v156
	v_add_u32_e32 v129, v110, v157
	v_add_u32_e32 v185, v110, v158
	v_add_u32_e32 v201, v110, v159
	v_pk_mul_f32 v[2:3], v[2:3], v[0:1] op_sel_hi:[1,0]
	v_pk_mul_f32 v[4:5], v[4:5], v[0:1] op_sel_hi:[1,0]
	v_add_u32_e32 v232, v110, v160
	v_add_u32_e32 v104, v110, v164
	v_add_u32_e32 v233, v110, v161
	v_add_u32_e32 v100, v110, v165
	v_add_u32_e32 v234, v110, v162
	v_add_u32_e32 v101, v110, v163
	s_waitcnt vmcnt(11)
	v_pk_mul_f32 v[34:35], v[34:35], v[54:55]
	v_pk_mul_f32 v[54:55], v[62:63], v[0:1] op_sel_hi:[1,0]
	v_cvt_pk_bf16_f32 v34, v34, v35
	v_pk_mul_f32 v[36:37], v[36:37], v[54:55]
	s_waitcnt vmcnt(3)
	v_pk_mul_f32 v[2:3], v[138:139], v[2:3]
	v_cvt_pk_bf16_f32 v35, v36, v37
	ds_write_b64 v127, v[34:35]
	v_pk_mul_f32 v[34:35], v[76:77], v[0:1] op_sel_hi:[1,0]
	v_pk_mul_f32 v[4:5], v[140:141], v[4:5]
	v_pk_mul_f32 v[14:15], v[14:15], v[34:35]
	v_pk_mul_f32 v[34:35], v[74:75], v[0:1] op_sel_hi:[1,0]
	v_cvt_pk_bf16_f32 v14, v14, v15
	v_pk_mul_f32 v[16:17], v[16:17], v[34:35]
	v_cvt_pk_bf16_f32 v2, v2, v3
	v_cvt_pk_bf16_f32 v15, v16, v17
	ds_write_b64 v129, v[14:15]
	v_pk_mul_f32 v[14:15], v[80:81], v[0:1] op_sel_hi:[1,0]
	v_pk_mul_f32 v[16:17], v[78:79], v[0:1] op_sel_hi:[1,0]
	v_pk_mul_f32 v[14:15], v[42:43], v[14:15]
	v_pk_mul_f32 v[16:17], v[44:45], v[16:17]
	v_cvt_pk_bf16_f32 v14, v14, v15
	v_cvt_pk_bf16_f32 v15, v16, v17
	ds_write_b64 v185, v[14:15]
	v_pk_mul_f32 v[14:15], v[84:85], v[0:1] op_sel_hi:[1,0]
	v_pk_mul_f32 v[16:17], v[82:83], v[0:1] op_sel_hi:[1,0]
	v_pk_mul_f32 v[14:15], v[38:39], v[14:15]
	v_pk_mul_f32 v[16:17], v[40:41], v[16:17]
	v_cvt_pk_bf16_f32 v14, v14, v15
	v_cvt_pk_bf16_f32 v15, v16, v17
	ds_write_b64 v201, v[14:15]
	v_pk_mul_f32 v[14:15], v[88:89], v[0:1] op_sel_hi:[1,0]
	v_pk_mul_f32 v[16:17], v[86:87], v[0:1] op_sel_hi:[1,0]
	v_pk_mul_f32 v[14:15], v[46:47], v[14:15]
	v_pk_mul_f32 v[16:17], v[48:49], v[16:17]
	v_cvt_pk_bf16_f32 v14, v14, v15
	v_cvt_pk_bf16_f32 v15, v16, v17
	v_cvt_pk_bf16_f32 v3, v4, v5
	ds_write_b64 v232, v[14:15]
	v_pk_mul_f32 v[14:15], v[22:23], v[0:1] op_sel_hi:[1,0]
	v_pk_mul_f32 v[16:17], v[24:25], v[0:1] op_sel_hi:[1,0]
	ds_write_b64 v104, v[2:3]
	v_pk_mul_f32 v[2:3], v[6:7], v[0:1] op_sel_hi:[1,0]
	v_pk_mul_f32 v[4:5], v[8:9], v[0:1] op_sel_hi:[1,0]
	v_pk_mul_f32 v[14:15], v[18:19], v[14:15]
	v_pk_mul_f32 v[16:17], v[20:21], v[16:17]
	s_waitcnt vmcnt(2)
	v_pk_mul_f32 v[2:3], v[186:187], v[2:3]
	v_pk_mul_f32 v[4:5], v[188:189], v[4:5]
	v_cvt_pk_bf16_f32 v14, v14, v15
	v_cvt_pk_bf16_f32 v15, v16, v17
	v_cvt_pk_bf16_f32 v2, v2, v3
	v_cvt_pk_bf16_f32 v3, v4, v5
	ds_write_b64 v233, v[14:15]
	v_pk_mul_f32 v[14:15], v[26:27], v[0:1] op_sel_hi:[1,0]
	v_pk_mul_f32 v[16:17], v[28:29], v[0:1] op_sel_hi:[1,0]
	ds_write_b64 v100, v[2:3]
	v_pk_mul_f32 v[2:3], v[10:11], v[0:1] op_sel_hi:[1,0]
	v_pk_mul_f32 v[4:5], v[12:13], v[0:1] op_sel_hi:[1,0]
	v_pk_mul_f32 v[14:15], v[130:131], v[14:15]
	v_pk_mul_f32 v[16:17], v[132:133], v[16:17]
	s_waitcnt vmcnt(1)
	v_pk_mul_f32 v[2:3], v[190:191], v[2:3]
	v_pk_mul_f32 v[4:5], v[192:193], v[4:5]
	v_cvt_pk_bf16_f32 v14, v14, v15
	v_cvt_pk_bf16_f32 v15, v16, v17
	v_cvt_pk_bf16_f32 v2, v2, v3
	v_cvt_pk_bf16_f32 v3, v4, v5
	v_add_u32_e32 v4, v110, v166
	ds_write_b64 v234, v[14:15]
	v_pk_mul_f32 v[14:15], v[30:31], v[0:1] op_sel_hi:[1,0]
	v_pk_mul_f32 v[16:17], v[32:33], v[0:1] op_sel_hi:[1,0]
	ds_write_b64 v4, v[2:3]
	v_pk_mul_f32 v[2:3], v[70:71], v[0:1] op_sel_hi:[1,0]
	v_pk_mul_f32 v[4:5], v[72:73], v[0:1] op_sel_hi:[1,0]
	v_pk_mul_f32 v[14:15], v[134:135], v[14:15]
	v_pk_mul_f32 v[16:17], v[136:137], v[16:17]
	s_waitcnt vmcnt(0)
	v_pk_mul_f32 v[2:3], v[50:51], v[2:3]
	v_pk_mul_f32 v[4:5], v[52:53], v[4:5]
	v_cvt_pk_bf16_f32 v14, v14, v15
	v_cvt_pk_bf16_f32 v15, v16, v17
	v_cvt_pk_bf16_f32 v2, v2, v3
	v_cvt_pk_bf16_f32 v3, v4, v5
	v_add_u32_e32 v0, v110, v167
	ds_write_b64 v101, v[14:15]
	ds_write_b64 v0, v[2:3]
	s_branch .LBB0_383
